# P9 tasks re-mapped onto the workgroup's own P8 q tiles; grid barrier P8->P9 replaced by the workgroup barrier (when gridDim==256)
# baseline (speedup 1.0000x reference)
; __device__ __forceinline__ unsigned xb_ld(unsigned* p)              { return __hip_atomic_load(p, __ATOMIC_RELAXED, __HIP_MEMORY_SCOPE_AGENT); }
; __device__ __forceinline__ unsigned xb_add(unsigned* p, unsigned v) { return __hip_atomic_fetch_add(p, v, __ATOMIC_RELAXED, __HIP_MEMORY_SCOPE_AGENT); }
; #define XB_SPIN(cond, bar) do { unsigned _sp = 0; while (cond) { __builtin_amdgcn_s_sleep(1); \
;     if ((++_sp & 255u) == 0u) { if (xb_ld(&(bar)[XB_TMO])) break; if (_sp > XB_SPIN_CAP) { atomicAdd(&(bar)[XB_TMO], 1u); break; } } } } while (0)
; __device__ __forceinline__ void xcd_barrier(const XcdBarrier& b) {
;     asm volatile("s_waitcnt vmcnt(0)" ::: "memory");
;     __syncthreads();
;     if (threadIdx.x == 0) {
;         unsigned* bar = b.bar;
;         __builtin_amdgcn_s_waitcnt(0);
;         unsigned nloc = b.st[0], nx = b.st[1];
;         if (nloc == 0u) { xcd_barrier_complete(bar, b.x, nloc, nx); b.st[0] = nloc; b.st[1] = nx; }
;         const unsigned old = xb_add(&bar[XB_XSUB(b.x)], 1u);
;         const unsigned gen = old / nloc;
;         if (old + 1u == (gen + 1u) * nloc) {
;             __builtin_amdgcn_fence(__ATOMIC_RELEASE, "agent");
;             asm volatile("s_waitcnt vmcnt(0)" ::: "memory");
;             const unsigned og = xb_add(&bar[XB_TOP], 1u);
;             const unsigned tg = og / nx;
;             if (og + 1u == (tg + 1u) * nx) xb_add(&bar[XB_TOPGEN], 1u);
;             else XB_SPIN(xb_ld(&bar[XB_TOPGEN]) == tg, bar);
;             __builtin_amdgcn_fence(__ATOMIC_ACQUIRE, "agent");
;             xb_add(&bar[XB_XGEN(b.x)], 1u);
;             asm volatile("s_waitcnt vmcnt(0)" ::: "memory");
;         } else {
;             XB_SPIN(xb_ld(&bar[XB_XGEN(b.x)]) == gen, bar);
;             __builtin_amdgcn_fence(__ATOMIC_ACQUIRE, "agent");
;             asm volatile("s_waitcnt vmcnt(0)" ::: "memory");
;         }
;     }
;     __syncthreads();
; }
.LBB0_758:
	s_cmp_gt_i32 s95, 9
	s_cselect_b64 s[0:1], -1, 0
	s_and_b64 s[2:3], s[8:9], s[0:1]
	s_andn2_b64 vcc, exec, s[2:3]
	s_cbranch_vccnz .LBB0_812
	s_waitcnt vmcnt(0)
	s_waitcnt vmcnt(0) lgkmcnt(0)
	s_barrier
	s_cmp_eq_u32 s84, 0x100
	s_cbranch_scc1 .LBB0_812
	s_and_saveexec_b64 s[2:3], s[82:83]
	s_cbranch_execz .LBB0_811
	s_add_i32 s4, 0, 0x23fc0
	v_mov_b32_e32 v0, s4
	s_waitcnt vmcnt(0) expcnt(0) lgkmcnt(0)
	ds_read_b32 v2, v0
	s_add_i32 s4, 0, 0x23fc4
	v_mov_b32_e32 v0, s4
	ds_read_b32 v0, v0
	s_waitcnt lgkmcnt(1)
	v_cmp_ne_u32_e32 vcc, 0, v2
	s_cbranch_vccnz .LBB0_775
	s_load_dwordx2 s[10:11], s[78:79], 0x4
	s_add_u32 s4, s92, 0x1000
	s_addc_u32 s5, s93, 0
	s_add_u32 s8, s92, 0x1100
	s_addc_u32 s9, s93, 0
	s_waitcnt lgkmcnt(0)
	s_mul_i32 s20, s10, s84
	s_add_u32 s10, s92, 0x1200
	s_mul_i32 s20, s20, s11
	s_addc_u32 s11, s93, 0
	s_add_u32 s12, s92, 0x1300
	s_addc_u32 s13, s93, 0
	s_mov_b32 s21, 1
	v_mov_b32_e32 v16, 0
	s_branch .LBB0_763

; __global__ void __launch_bounds__(NT, 2) mk_fwd(Args args) {
;     ...
;     if (IN(9)) REPS(9) {
;         float* scr = (float*)(lds + wave * 8704);
;         for (int task_ = gw; task_ < (MTOK / 64) * 8 * RMUL(9); task_ += NGW) {
;             const int task = task_ & 2047; const int tt = task >> 3, h = task & 7;
;             int T0[16], T1[16];
; #pragma unroll
;             for (int p = 0; p < 2; ++p) {
;                 int T[16];
; #pragma unroll
;                 for (int j = 0; j < 16; ++j) T[j] = (int)0xff7fffff;
;                 const bf16* qa = Q + (size_t)(tt * 64 + (lane & 31)) * DM + h * 256 + p * 128 + (lane >> 5) * 8;
;                 for (int nc = 0; nc < 4; ++nc) {
;                     f32x16 acc[2];
; #pragma unroll
;                     for (int mt = 0; mt < 2; ++mt)
; #pragma unroll
;                         for (int r = 0; r < 16; ++r) acc[mt][r] = 0.f;
;                     const bf16* kb = KEYSB + ((size_t)(h * 2 + p) * 128 + nc * 32 + (lane & 31)) * 128 + (lane >> 5) * 8;
.LBB0_812:
	s_cmp_lt_i32 s94, 10
	s_cselect_b64 s[2:3], -1, 0
	s_add_u32 s46, s92, 0x16a00000
	s_addc_u32 s47, s93, 0
	s_add_u32 s48, s92, 0x17200000
	s_addc_u32 s49, s93, 0
	s_and_b64 s[20:21], s[2:3], s[0:1]
	s_andn2_b64 vcc, exec, s[20:21]
	s_cbranch_vccnz .LBB0_829
	v_writelane_b32 v249, s20, 33
	s_mov_b32 s0, s70
	s_cmpk_gt_i32 s70, 0x7ff
	v_writelane_b32 v249, s21, 34
	v_writelane_b32 v249, s86, 27
	s_nop 1
	v_writelane_b32 v249, s87, 28
	v_writelane_b32 v249, s82, 29
	s_nop 1
	v_writelane_b32 v249, s83, 30
	v_writelane_b32 v249, s78, 35
	s_nop 1
	v_writelane_b32 v249, s79, 36
	v_writelane_b32 v249, s77, 37
	v_writelane_b32 v249, s74, 38
	s_nop 1
	v_writelane_b32 v249, s75, 39
	v_writelane_b32 v249, s0, 40
	s_nop 1
	v_writelane_b32 v249, s1, 41
	s_cbranch_scc1 .LBB0_824
	v_lshrrev_b32_e32 v4, 5, v128
	s_mul_i32 s0, s85, 0x2200
	v_lshlrev_b32_e32 v32, 4, v4
	v_mov_b32_e32 v33, 0
	s_add_i32 s2, s0, 0
	s_waitcnt vmcnt(0)
	v_and_b32_e32 v2, 31, v168
	v_lshl_add_u64 v[0:1], s[92:93], 0, v[32:33]
	s_mov_b64 s[0:1], 0x200000
	v_lshl_add_u64 v[34:35], v[0:1], 0, s[0:1]
	v_mov_b32_e32 v0, s2
	v_lshl_add_u32 v1, v2, 2, s2
	s_movk_i32 s0, 0x84
	s_and_b32 s2, s85, 7
	s_cmp_eq_u32 s84, 0x100
	s_cbranch_scc0 .Lp9_map_a
	s_lshr_b32 s98, s70, 9
	s_and_b32 s99, s85, 4
	s_add_i32 s2, s98, s99
.Lp9_map_a:
	v_mad_u32_u24 v56, v128, s0, v0
	s_lshl_b32 s0, s2, 9
	s_add_u32 s0, s6, s0
	s_addc_u32 s1, s7, 0
	v_lshl_add_u64 v[36:37], s[0:1], 0, v[32:33]
	s_lshl_b32 s0, s2, 4
	v_lshlrev_b32_e32 v3, 11, v2
	v_lshl_or_b32 v57, s2, 8, v2
	v_lshl_or_b32 v2, v128, 7, s0
	v_readlane_b32 s0, v249, 40
	v_readlane_b32 s1, v249, 41
	v_writelane_b32 v249, s72, 25
	v_mul_u32_u24_e32 v0, 0x210, v4
	v_add_u32_e32 v60, v1, v0
	v_writelane_b32 v249, s73, 26
	v_writelane_b32 v249, s46, 31
	v_or_b32_e32 v58, 0x80, v57
	v_lshlrev_b32_e32 v59, 1, v3
	v_writelane_b32 v249, s47, 32
	s_mov_b32 s33, 0xff61b1e6
	s_movk_i32 s96, 0x3fff
	v_lshlrev_b32_e32 v61, 2, v2
	v_add_u32_e32 v62, 0x400, v60
	v_add_u32_e32 v63, 0x800, v60
	v_add_u32_e32 v64, 0xc00, v60
	v_add_u32_e32 v65, 0x1000, v60
	v_add_u32_e32 v66, 0x1400, v60
	v_add_u32_e32 v67, 0x1800, v60
	v_add_u32_e32 v68, 0x1c00, v60
	s_mov_b32 s97, s0
	s_cmp_eq_u32 s84, 0x100
	s_cbranch_scc0 .Lp9_map_b
	s_lshr_b32 s98, s0, 3
	s_and_b32 s99, s98, 7
	s_lshl_b32 s99, s99, 3
	s_bfe_u32 s98, s98, 0x30003
	s_add_i32 s99, s99, s98
	s_lshl_b32 s99, s99, 2
	s_and_b32 s98, s85, 3
	s_add_i32 s99, s99, s98
	s_lshl_b32 s97, s99, 3
.Lp9_map_b:
	v_writelane_b32 v249, s48, 42
	s_nop 1
	v_writelane_b32 v249, s49, 43

; __global__ void __launch_bounds__(NT, 2) mk_fwd(Args args) {
	.amdhsa_kernel _Z6mk_fwd4Args
		.amdhsa_group_segment_fixed_size 0
		.amdhsa_private_segment_fixed_size 0
		.amdhsa_kernarg_size 512
		.amdhsa_user_sgpr_count 2
		.amdhsa_user_sgpr_dispatch_ptr 0
		.amdhsa_user_sgpr_queue_ptr 0
		.amdhsa_user_sgpr_kernarg_segment_ptr 1
		.amdhsa_user_sgpr_dispatch_id 0
		.amdhsa_user_sgpr_kernarg_preload_length 0
		.amdhsa_user_sgpr_kernarg_preload_offset 0
		.amdhsa_user_sgpr_private_segment_size 0
		.amdhsa_uses_dynamic_stack 0
		.amdhsa_enable_private_segment 0
		.amdhsa_system_sgpr_workgroup_id_x 1
		.amdhsa_system_sgpr_workgroup_id_y 0
		.amdhsa_system_sgpr_workgroup_id_z 0
		.amdhsa_system_sgpr_workgroup_info 0
		.amdhsa_system_vgpr_workitem_id 2
		.amdhsa_next_free_vgpr 250
		.amdhsa_next_free_sgpr 100
		.amdhsa_accum_offset 252
		.amdhsa_reserve_vcc 1
		.amdhsa_float_round_mode_32 0
		.amdhsa_float_round_mode_16_64 0
		.amdhsa_float_denorm_mode_32 3
		.amdhsa_float_denorm_mode_16_64 3
		.amdhsa_dx10_clamp 1
		.amdhsa_ieee_mode 1
		.amdhsa_fp16_overflow 0
		.amdhsa_tg_split 0
		.amdhsa_exception_fp_ieee_invalid_op 0
		.amdhsa_exception_fp_denorm_src 0
		.amdhsa_exception_fp_ieee_div_zero 0
		.amdhsa_exception_fp_ieee_overflow 0
		.amdhsa_exception_fp_ieee_underflow 0
		.amdhsa_exception_fp_ieee_inexact 0
		.amdhsa_exception_int_div_zero 0
	.end_amdhsa_kernel

; __global__ void __launch_bounds__(NT, 2) mk_fwd(Args args) {
amdhsa.kernels:
  - .agpr_count:     0
    .args:
      - .offset:         0
        .size:           256
        .value_kind:     by_value
      - .offset:         256
        .size:           4
        .value_kind:     hidden_block_count_x
      - .offset:         260
        .size:           4
        .value_kind:     hidden_block_count_y
      - .offset:         264
        .size:           4
        .value_kind:     hidden_block_count_z
      - .offset:         268
        .size:           2
        .value_kind:     hidden_group_size_x
      - .offset:         270
        .size:           2
        .value_kind:     hidden_group_size_y
      - .offset:         272
        .size:           2
        .value_kind:     hidden_group_size_z
      - .offset:         274
        .size:           2
        .value_kind:     hidden_remainder_x
      - .offset:         276
        .size:           2
        .value_kind:     hidden_remainder_y
      - .offset:         278
        .size:           2
        .value_kind:     hidden_remainder_z
      - .offset:         296
        .size:           8
        .value_kind:     hidden_global_offset_x
      - .offset:         304
        .size:           8
        .value_kind:     hidden_global_offset_y
      - .offset:         312
        .size:           8
        .value_kind:     hidden_global_offset_z
      - .offset:         320
        .size:           2
        .value_kind:     hidden_grid_dims
      - .offset:         344
        .size:           8
        .value_kind:     hidden_multigrid_sync_arg
      - .offset:         376
        .size:           4
        .value_kind:     hidden_dynamic_lds_size
    .group_segment_fixed_size: 0
    .kernarg_segment_align: 8
    .kernarg_segment_size: 512
    .language:       OpenCL C
    .language_version:
      - 2
      - 0
    .max_flat_workgroup_size: 512
    .name:           _Z6mk_fwd4Args
    .private_segment_fixed_size: 0
    .sgpr_count:     106
    .sgpr_spill_count: 53
    .symbol:         _Z6mk_fwd4Args.kd
    .uniform_work_group_size: 1
    .uses_dynamic_stack: false
    .vgpr_count:     250
    .vgpr_spill_count: 0
    .wavefront_size: 64
